# hybatch
# speedup vs baseline: 1.0010x; 1.0002x over previous
.LBB0_199:
	s_or_b64 exec, exec, s[40:41]
	s_waitcnt vmcnt(0)
	ds_bpermute_b32 v101, v125, v58
	ds_bpermute_b32 v102, v125, v59
	ds_bpermute_b32 v103, v125, v60
	ds_bpermute_b32 v104, v125, v61
	ds_bpermute_b32 v105, v125, v78
	ds_bpermute_b32 v106, v125, v79
	ds_bpermute_b32 v107, v125, v80
	ds_bpermute_b32 v108, v125, v81
	ds_bpermute_b32 v109, v125, v82
	ds_bpermute_b32 v110, v125, v83
	ds_bpermute_b32 v111, v125, v84
	ds_bpermute_b32 v112, v125, v85
	ds_bpermute_b32 v113, v126, v58
	ds_bpermute_b32 v114, v126, v59
	ds_bpermute_b32 v115, v126, v60
	ds_bpermute_b32 v116, v126, v61
	ds_bpermute_b32 v117, v126, v78
	ds_bpermute_b32 v118, v126, v79
	ds_bpermute_b32 v119, v126, v80
	ds_bpermute_b32 v120, v126, v81
	ds_bpermute_b32 v121, v126, v82
	ds_bpermute_b32 v122, v126, v83
	ds_bpermute_b32 v123, v126, v84
	ds_bpermute_b32 v124, v126, v85
	s_mov_b64 vcc, 3
	s_waitcnt lgkmcnt(12)
	v_cndmask_b32_e32 v54, v101, v54, vcc
	v_cndmask_b32_e32 v55, v102, v55, vcc
	v_cndmask_b32_e32 v56, v103, v56, vcc
	v_cndmask_b32_e32 v57, v104, v57, vcc
	v_cndmask_b32_e32 v66, v105, v66, vcc
	v_cndmask_b32_e32 v67, v106, v67, vcc
	v_cndmask_b32_e32 v68, v107, v68, vcc
	v_cndmask_b32_e32 v69, v108, v69, vcc
	v_cndmask_b32_e32 v74, v109, v74, vcc
	v_cndmask_b32_e32 v75, v110, v75, vcc
	v_cndmask_b32_e32 v76, v111, v76, vcc
	v_cndmask_b32_e32 v77, v112, v77, vcc
	s_mov_b32 vcc_lo, 0
	s_mov_b32 vcc_hi, 0xc0000000
	s_waitcnt lgkmcnt(0)
	v_cndmask_b32_e32 v50, v113, v50, vcc
	v_cndmask_b32_e32 v51, v114, v51, vcc
	v_cndmask_b32_e32 v52, v115, v52, vcc
	v_cndmask_b32_e32 v53, v116, v53, vcc
	v_cndmask_b32_e32 v62, v117, v62, vcc
	v_cndmask_b32_e32 v63, v118, v63, vcc
	v_cndmask_b32_e32 v64, v119, v64, vcc
	v_cndmask_b32_e32 v65, v120, v65, vcc
	v_cndmask_b32_e32 v70, v121, v70, vcc
	v_cndmask_b32_e32 v71, v122, v71, vcc
	v_cndmask_b32_e32 v72, v123, v72, vcc
	v_cndmask_b32_e32 v73, v124, v73, vcc
	s_waitcnt vmcnt(2)
	v_pk_mul_f32 v[58:59], v[42:43], v[58:59]
	v_pk_mul_f32 v[60:61], v[44:45], v[60:61]
	v_pk_fma_f32 v[54:55], v[34:35], v[54:55], v[58:59]
	v_ashrrev_i32_e32 v58, s14, v100
	v_mul_lo_u32 v58, v58, s6
	s_waitcnt vmcnt(1)
	v_pk_mul_f32 v[78:79], v[10:11], v[78:79]
	v_pk_fma_f32 v[56:57], v[36:37], v[56:57], v[60:61]
	v_pk_fma_f32 v[50:51], v[6:7], v[50:51], v[54:55]
	v_lshlrev_b32_e32 v58, 2, v58
	v_lshlrev_b32_e32 v60, 1, v99
	v_pk_fma_f32 v[66:67], v[26:27], v[66:67], v[78:79]
	v_pk_fma_f32 v[52:53], v[8:9], v[52:53], v[56:57]
	v_pk_add_f32 v[50:51], v[2:3], v[50:51]
	s_waitcnt vmcnt(0)
	v_pk_mul_f32 v[56:57], v[38:39], v[82:83]
	v_add3_u32 v58, v95, v58, v60
	v_pk_fma_f32 v[62:63], v[14:15], v[62:63], v[66:67]
	v_pk_fma_f32 v[56:57], v[30:31], v[74:75], v[56:57]
	v_cvt_pk_bf16_f32 v50, v50, v1
	v_add_u32_e32 v60, s6, v58
	v_pk_add_f32 v[62:63], v[18:19], v[62:63]
	v_pk_fma_f32 v[56:57], v[46:47], v[70:71], v[56:57]
	v_mov_b32_e32 v59, s6
	v_cmp_le_i32_e32 vcc, s9, v99
	ds_write_b16 v60, v50
	v_cvt_pk_bf16_f32 v50, v62, v1
	v_pk_add_f32 v[56:57], v[22:23], v[56:57]
	v_cndmask_b32_e32 v59, 0, v59, vcc
	ds_write_b16 v97, v50 offset:13312
	v_cvt_pk_bf16_f32 v50, v56, v1
	ds_write_b16 v97, v50 offset:15360
	v_lshl_add_u32 v50, v59, 1, v58
	v_cvt_pk_bf16_f32 v51, v51, v1
	v_pk_mul_f32 v[80:81], v[12:13], v[80:81]
	ds_write_b16 v50, v1
	ds_write_b16 v50, v1 offset:4096
	ds_write_b16 v60, v51 offset:16896
	v_cvt_pk_bf16_f32 v51, v63, v1
	v_pk_fma_f32 v[68:69], v[28:29], v[68:69], v[80:81]
	v_pk_mul_f32 v[54:55], v[40:41], v[84:85]
	ds_write_b16 v97, v51 offset:30208
	v_cvt_pk_bf16_f32 v51, v57, v1
	v_pk_fma_f32 v[64:65], v[16:17], v[64:65], v[68:69]
	v_pk_add_f32 v[52:53], v[4:5], v[52:53]
	v_pk_fma_f32 v[54:55], v[32:33], v[76:77], v[54:55]
	ds_write_b16 v97, v51 offset:32256
	ds_write_b16 v50, v1 offset:16896
	ds_write_b16 v50, v1 offset:20992
	v_cvt_pk_bf16_f32 v51, v52, v1
	v_pk_add_f32 v[64:65], v[20:21], v[64:65]
	v_pk_fma_f32 v[54:55], v[48:49], v[72:73], v[54:55]
	ds_write_b16 v60, v51 offset:33792
	v_cvt_pk_bf16_f32 v51, v64, v1
	v_pk_add_f32 v[54:55], v[24:25], v[54:55]
	ds_write_b16 v97, v51 offset:47104
	v_cvt_pk_bf16_f32 v51, v54, v1
	ds_write_b16 v97, v51 offset:49152
	ds_write_b16 v50, v1 offset:33792
	ds_write_b16 v50, v1 offset:37888
	v_cvt_pk_bf16_f32 v51, v53, v1
	s_add_u32 s24, s24, 0x600000
	ds_write_b16 v60, v51 offset:50688
	v_cvt_pk_bf16_f32 v51, v65, v1
	s_addc_u32 s25, s25, 0
	ds_write_b16 v97, v51 offset:64000
	v_cvt_pk_bf16_f32 v51, v55, v1
	v_add_u32_e32 v52, 0x10200, v97
	v_add_u32_e32 v98, 0x200, v98
	s_cmp_eq_u32 s24, 0xc00000
	v_add_u32_e32 v97, 0x400, v97
	ds_write_b16 v52, v51
	ds_write_b16 v50, v1 offset:50688
	ds_write_b16 v50, v1 offset:54784
	s_cbranch_scc1 .LBB0_224

.LBB0_212:
	s_or_b64 exec, exec, s[40:41]
	s_waitcnt vmcnt(0)
	ds_bpermute_b32 v101, v125, v58
	ds_bpermute_b32 v102, v125, v59
	ds_bpermute_b32 v103, v125, v60
	ds_bpermute_b32 v104, v125, v61
	ds_bpermute_b32 v105, v125, v78
	ds_bpermute_b32 v106, v125, v79
	ds_bpermute_b32 v107, v125, v80
	ds_bpermute_b32 v108, v125, v81
	ds_bpermute_b32 v109, v125, v82
	ds_bpermute_b32 v110, v125, v83
	ds_bpermute_b32 v111, v125, v84
	ds_bpermute_b32 v112, v125, v85
	ds_bpermute_b32 v113, v126, v58
	ds_bpermute_b32 v114, v126, v59
	ds_bpermute_b32 v115, v126, v60
	ds_bpermute_b32 v116, v126, v61
	ds_bpermute_b32 v117, v126, v78
	ds_bpermute_b32 v118, v126, v79
	ds_bpermute_b32 v119, v126, v80
	ds_bpermute_b32 v120, v126, v81
	ds_bpermute_b32 v121, v126, v82
	ds_bpermute_b32 v122, v126, v83
	ds_bpermute_b32 v123, v126, v84
	ds_bpermute_b32 v124, v126, v85
	s_mov_b64 vcc, 3
	s_waitcnt lgkmcnt(12)
	v_cndmask_b32_e32 v54, v101, v54, vcc
	v_cndmask_b32_e32 v55, v102, v55, vcc
	v_cndmask_b32_e32 v56, v103, v56, vcc
	v_cndmask_b32_e32 v57, v104, v57, vcc
	v_cndmask_b32_e32 v66, v105, v66, vcc
	v_cndmask_b32_e32 v67, v106, v67, vcc
	v_cndmask_b32_e32 v68, v107, v68, vcc
	v_cndmask_b32_e32 v69, v108, v69, vcc
	v_cndmask_b32_e32 v74, v109, v74, vcc
	v_cndmask_b32_e32 v75, v110, v75, vcc
	v_cndmask_b32_e32 v76, v111, v76, vcc
	v_cndmask_b32_e32 v77, v112, v77, vcc
	s_mov_b32 vcc_lo, 0
	s_mov_b32 vcc_hi, 0xc0000000
	s_waitcnt lgkmcnt(0)
	v_cndmask_b32_e32 v50, v113, v50, vcc
	v_cndmask_b32_e32 v51, v114, v51, vcc
	v_cndmask_b32_e32 v52, v115, v52, vcc
	v_cndmask_b32_e32 v53, v116, v53, vcc
	v_cndmask_b32_e32 v62, v117, v62, vcc
	v_cndmask_b32_e32 v63, v118, v63, vcc
	v_cndmask_b32_e32 v64, v119, v64, vcc
	v_cndmask_b32_e32 v65, v120, v65, vcc
	v_cndmask_b32_e32 v70, v121, v70, vcc
	v_cndmask_b32_e32 v71, v122, v71, vcc
	v_cndmask_b32_e32 v72, v123, v72, vcc
	v_cndmask_b32_e32 v73, v124, v73, vcc
	s_waitcnt vmcnt(2)
	v_pk_mul_f32 v[58:59], v[42:43], v[58:59]
	v_pk_mul_f32 v[60:61], v[44:45], v[60:61]
	v_pk_fma_f32 v[54:55], v[34:35], v[54:55], v[58:59]
	v_ashrrev_i32_e32 v58, s14, v98
	v_mul_lo_u32 v58, v58, s6
	s_waitcnt vmcnt(1)
	v_pk_mul_f32 v[78:79], v[10:11], v[78:79]
	v_pk_fma_f32 v[56:57], v[36:37], v[56:57], v[60:61]
	v_pk_fma_f32 v[50:51], v[6:7], v[50:51], v[54:55]
	v_lshlrev_b32_e32 v58, 2, v58
	v_lshlrev_b32_e32 v60, 1, v99
	v_pk_fma_f32 v[66:67], v[26:27], v[66:67], v[78:79]
	v_pk_fma_f32 v[52:53], v[8:9], v[52:53], v[56:57]
	v_pk_add_f32 v[50:51], v[2:3], v[50:51]
	s_waitcnt vmcnt(0)
	v_pk_mul_f32 v[56:57], v[38:39], v[82:83]
	v_add3_u32 v58, v95, v58, v60
	v_pk_fma_f32 v[62:63], v[14:15], v[62:63], v[66:67]
	v_pk_fma_f32 v[56:57], v[30:31], v[74:75], v[56:57]
	v_cvt_pk_bf16_f32 v50, v50, v1
	v_add_u32_e32 v60, s6, v58
	v_pk_add_f32 v[62:63], v[18:19], v[62:63]
	v_pk_fma_f32 v[56:57], v[46:47], v[70:71], v[56:57]
	v_mov_b32_e32 v59, s6
	v_cmp_le_i32_e32 vcc, s9, v99
	ds_write_b16 v60, v50
	v_cvt_pk_bf16_f32 v50, v62, v1
	v_pk_add_f32 v[56:57], v[22:23], v[56:57]
	v_cndmask_b32_e32 v59, 0, v59, vcc
	ds_write_b16 v97, v50 offset:12800
	v_cvt_pk_bf16_f32 v50, v56, v1
	ds_write_b16 v97, v50 offset:14848
	v_lshl_add_u32 v50, v59, 1, v58
	v_cvt_pk_bf16_f32 v51, v51, v1
	v_pk_mul_f32 v[80:81], v[12:13], v[80:81]
	ds_write_b16 v50, v1
	ds_write_b16 v50, v1 offset:4096
	ds_write_b16 v60, v51 offset:16896
	v_cvt_pk_bf16_f32 v51, v63, v1
	v_pk_fma_f32 v[68:69], v[28:29], v[68:69], v[80:81]
	v_pk_mul_f32 v[54:55], v[40:41], v[84:85]
	ds_write_b16 v97, v51 offset:29696
	v_cvt_pk_bf16_f32 v51, v57, v1
	v_pk_fma_f32 v[64:65], v[16:17], v[64:65], v[68:69]
	v_pk_add_f32 v[52:53], v[4:5], v[52:53]
	v_pk_fma_f32 v[54:55], v[32:33], v[76:77], v[54:55]
	ds_write_b16 v97, v51 offset:31744
	ds_write_b16 v50, v1 offset:16896
	ds_write_b16 v50, v1 offset:20992
	v_cvt_pk_bf16_f32 v51, v52, v1
	v_pk_add_f32 v[64:65], v[20:21], v[64:65]
	v_pk_fma_f32 v[54:55], v[48:49], v[72:73], v[54:55]
	ds_write_b16 v60, v51 offset:33792
	v_cvt_pk_bf16_f32 v51, v64, v1
	v_pk_add_f32 v[54:55], v[24:25], v[54:55]
	ds_write_b16 v97, v51 offset:46592
	v_cvt_pk_bf16_f32 v51, v54, v1
	ds_write_b16 v97, v51 offset:48640
	ds_write_b16 v50, v1 offset:33792
	ds_write_b16 v50, v1 offset:37888
	v_cvt_pk_bf16_f32 v51, v53, v1
	ds_write_b16 v60, v51 offset:50688
	v_cvt_pk_bf16_f32 v51, v65, v1
	v_add_u32_e32 v100, 0x100, v98
	ds_write_b16 v97, v51 offset:63488
	v_cvt_pk_bf16_f32 v51, v55, v1
	v_add_u32_e32 v52, 0x10000, v97
	v_and_b32_e32 v99, s17, v100
	ds_write_b16 v52, v51
	ds_write_b16 v50, v1 offset:50688
	ds_write_b16 v50, v1 offset:54784
	v_cmp_lt_i32_e64 s[40:41], 0, v99
	s_nop 1
	s_and_b64 s[40:41], s[40:41], 3
	v_mov_b32_e32 v50, 0
	v_mov_b32_e32 v54, 0
	v_mov_b32_e32 v55, 0
	v_mov_b32_e32 v56, 0
	v_mov_b32_e32 v57, 0
	s_and_saveexec_b64 s[42:43], s[40:41]
	s_cbranch_execz .LBB0_214
	v_add_co_u32_e32 v52, vcc, 0x264fd000, v92
	s_nop 1
	v_addc_co_u32_e32 v53, vcc, 0, v93, vcc
	global_load_dwordx4 v[54:57], v[52:53], off
